# bias2 wave sums: the eight interleaved ds_bpermute butterflies use DPP adds and v_permlane16/32_swap
# speedup vs baseline: 1.0098x; 1.0098x over previous
.Lb2_nonext:
	v_mul_f32_e32 v208, v4, v180
	v_mul_f32_e32 v209, v5, v181
	v_mul_f32_e32 v210, v6, v182
	v_mul_f32_e32 v211, v7, v183
	v_fmac_f32_e32 v208, v0, v176
	v_fmac_f32_e32 v209, v1, v177
	v_fmac_f32_e32 v210, v2, v178
	v_fmac_f32_e32 v211, v3, v179
	v_fmac_f32_e32 v208, v8, v184
	v_fmac_f32_e32 v209, v9, v185
	v_fmac_f32_e32 v210, v10, v186
	v_fmac_f32_e32 v211, v11, v187
	v_fmac_f32_e32 v208, v12, v188
	v_fmac_f32_e32 v209, v13, v189
	v_fmac_f32_e32 v210, v14, v190
	v_fmac_f32_e32 v211, v15, v191
	v_add_f32_e32 v208, v208, v209
	v_add_f32_e32 v209, v210, v211
	v_add_f32_e32 v200, v208, v209
	v_mul_f32_e32 v208, v20, v180
	v_mul_f32_e32 v209, v21, v181
	v_mul_f32_e32 v210, v22, v182
	v_mul_f32_e32 v211, v23, v183
	v_fmac_f32_e32 v208, v16, v176
	v_fmac_f32_e32 v209, v17, v177
	v_fmac_f32_e32 v210, v18, v178
	v_fmac_f32_e32 v211, v19, v179
	v_fmac_f32_e32 v208, v24, v184
	v_fmac_f32_e32 v209, v25, v185
	v_fmac_f32_e32 v210, v26, v186
	v_fmac_f32_e32 v211, v27, v187
	v_fmac_f32_e32 v208, v28, v188
	v_fmac_f32_e32 v209, v29, v189
	v_fmac_f32_e32 v210, v30, v190
	v_fmac_f32_e32 v211, v31, v191
	v_add_f32_e32 v208, v208, v209
	v_add_f32_e32 v209, v210, v211
	v_add_f32_e32 v201, v208, v209
	v_mul_f32_e32 v208, v36, v180
	v_mul_f32_e32 v209, v37, v181
	v_mul_f32_e32 v210, v38, v182
	v_mul_f32_e32 v211, v39, v183
	v_fmac_f32_e32 v208, v32, v176
	v_fmac_f32_e32 v209, v33, v177
	v_fmac_f32_e32 v210, v34, v178
	v_fmac_f32_e32 v211, v35, v179
	v_fmac_f32_e32 v208, v40, v184
	v_fmac_f32_e32 v209, v41, v185
	v_fmac_f32_e32 v210, v42, v186
	v_fmac_f32_e32 v211, v43, v187
	v_fmac_f32_e32 v208, v44, v188
	v_fmac_f32_e32 v209, v45, v189
	v_fmac_f32_e32 v210, v46, v190
	v_fmac_f32_e32 v211, v47, v191
	v_add_f32_e32 v208, v208, v209
	v_add_f32_e32 v209, v210, v211
	v_add_f32_e32 v202, v208, v209
	v_mul_f32_e32 v208, v52, v180
	v_mul_f32_e32 v209, v53, v181
	v_mul_f32_e32 v210, v54, v182
	v_mul_f32_e32 v211, v55, v183
	v_fmac_f32_e32 v208, v48, v176
	v_fmac_f32_e32 v209, v49, v177
	v_fmac_f32_e32 v210, v50, v178
	v_fmac_f32_e32 v211, v51, v179
	v_fmac_f32_e32 v208, v56, v184
	v_fmac_f32_e32 v209, v57, v185
	v_fmac_f32_e32 v210, v58, v186
	v_fmac_f32_e32 v211, v59, v187
	v_fmac_f32_e32 v208, v60, v188
	v_fmac_f32_e32 v209, v61, v189
	v_fmac_f32_e32 v210, v62, v190
	v_fmac_f32_e32 v211, v63, v191
	v_add_f32_e32 v208, v208, v209
	v_add_f32_e32 v209, v210, v211
	v_add_f32_e32 v203, v208, v209
	v_mul_f32_e32 v208, v68, v180
	v_mul_f32_e32 v209, v69, v181
	v_mul_f32_e32 v210, v70, v182
	v_mul_f32_e32 v211, v71, v183
	v_fmac_f32_e32 v208, v64, v176
	v_fmac_f32_e32 v209, v65, v177
	v_fmac_f32_e32 v210, v66, v178
	v_fmac_f32_e32 v211, v67, v179
	v_fmac_f32_e32 v208, v72, v184
	v_fmac_f32_e32 v209, v73, v185
	v_fmac_f32_e32 v210, v74, v186
	v_fmac_f32_e32 v211, v75, v187
	v_fmac_f32_e32 v208, v76, v188
	v_fmac_f32_e32 v209, v77, v189
	v_fmac_f32_e32 v210, v78, v190
	v_fmac_f32_e32 v211, v79, v191
	v_add_f32_e32 v208, v208, v209
	v_add_f32_e32 v209, v210, v211
	v_add_f32_e32 v204, v208, v209
	v_mul_f32_e32 v208, v84, v180
	v_mul_f32_e32 v209, v85, v181
	v_mul_f32_e32 v210, v86, v182
	v_mul_f32_e32 v211, v87, v183
	v_fmac_f32_e32 v208, v80, v176
	v_fmac_f32_e32 v209, v81, v177
	v_fmac_f32_e32 v210, v82, v178
	v_fmac_f32_e32 v211, v83, v179
	v_fmac_f32_e32 v208, v88, v184
	v_fmac_f32_e32 v209, v89, v185
	v_fmac_f32_e32 v210, v90, v186
	v_fmac_f32_e32 v211, v91, v187
	v_fmac_f32_e32 v208, v92, v188
	v_fmac_f32_e32 v209, v93, v189
	v_fmac_f32_e32 v210, v94, v190
	v_fmac_f32_e32 v211, v95, v191
	v_add_f32_e32 v208, v208, v209
	v_add_f32_e32 v209, v210, v211
	v_add_f32_e32 v205, v208, v209
	v_mul_f32_e32 v208, v100, v180
	v_mul_f32_e32 v209, v101, v181
	v_mul_f32_e32 v210, v102, v182
	v_mul_f32_e32 v211, v103, v183
	v_fmac_f32_e32 v208, v96, v176
	v_fmac_f32_e32 v209, v97, v177
	v_fmac_f32_e32 v210, v98, v178
	v_fmac_f32_e32 v211, v99, v179
	v_fmac_f32_e32 v208, v104, v184
	v_fmac_f32_e32 v209, v105, v185
	v_fmac_f32_e32 v210, v106, v186
	v_fmac_f32_e32 v211, v107, v187
	v_fmac_f32_e32 v208, v108, v188
	v_fmac_f32_e32 v209, v109, v189
	v_fmac_f32_e32 v210, v110, v190
	v_fmac_f32_e32 v211, v111, v191
	v_add_f32_e32 v208, v208, v209
	v_add_f32_e32 v209, v210, v211
	v_add_f32_e32 v206, v208, v209
	v_mul_f32_e32 v208, v116, v180
	v_mul_f32_e32 v209, v117, v181
	v_mul_f32_e32 v210, v118, v182
	v_mul_f32_e32 v211, v119, v183
	v_fmac_f32_e32 v208, v112, v176
	v_fmac_f32_e32 v209, v113, v177
	v_fmac_f32_e32 v210, v114, v178
	v_fmac_f32_e32 v211, v115, v179
	v_fmac_f32_e32 v208, v120, v184
	v_fmac_f32_e32 v209, v121, v185
	v_fmac_f32_e32 v210, v122, v186
	v_fmac_f32_e32 v211, v123, v187
	v_fmac_f32_e32 v208, v124, v188
	v_fmac_f32_e32 v209, v125, v189
	v_fmac_f32_e32 v210, v126, v190
	v_fmac_f32_e32 v211, v127, v191
	v_add_f32_e32 v208, v208, v209
	v_add_f32_e32 v209, v210, v211
	v_add_f32_e32 v207, v208, v209
	s_nop 1
	v_add_f32_dpp v200, v200, v200 quad_perm:[1,0,3,2] row_mask:0xf bank_mask:0xf
	s_nop 1
	v_add_f32_dpp v201, v201, v201 quad_perm:[1,0,3,2] row_mask:0xf bank_mask:0xf
	s_nop 1
	v_add_f32_dpp v202, v202, v202 quad_perm:[1,0,3,2] row_mask:0xf bank_mask:0xf
	s_nop 1
	v_add_f32_dpp v203, v203, v203 quad_perm:[1,0,3,2] row_mask:0xf bank_mask:0xf
	s_nop 1
	v_add_f32_dpp v204, v204, v204 quad_perm:[1,0,3,2] row_mask:0xf bank_mask:0xf
	s_nop 1
	v_add_f32_dpp v205, v205, v205 quad_perm:[1,0,3,2] row_mask:0xf bank_mask:0xf
	s_nop 1
	v_add_f32_dpp v206, v206, v206 quad_perm:[1,0,3,2] row_mask:0xf bank_mask:0xf
	s_nop 1
	v_add_f32_dpp v207, v207, v207 quad_perm:[1,0,3,2] row_mask:0xf bank_mask:0xf
	s_waitcnt lgkmcnt(7)
	s_waitcnt lgkmcnt(6)
	s_waitcnt lgkmcnt(5)
	s_waitcnt lgkmcnt(4)
	s_waitcnt lgkmcnt(3)
	s_waitcnt lgkmcnt(2)
	s_waitcnt lgkmcnt(1)
	s_waitcnt lgkmcnt(0)
	s_nop 1
	v_add_f32_dpp v200, v200, v200 quad_perm:[2,3,0,1] row_mask:0xf bank_mask:0xf
	s_nop 1
	v_add_f32_dpp v201, v201, v201 quad_perm:[2,3,0,1] row_mask:0xf bank_mask:0xf
	s_nop 1
	v_add_f32_dpp v202, v202, v202 quad_perm:[2,3,0,1] row_mask:0xf bank_mask:0xf
	s_nop 1
	v_add_f32_dpp v203, v203, v203 quad_perm:[2,3,0,1] row_mask:0xf bank_mask:0xf
	s_nop 1
	v_add_f32_dpp v204, v204, v204 quad_perm:[2,3,0,1] row_mask:0xf bank_mask:0xf
	s_nop 1
	v_add_f32_dpp v205, v205, v205 quad_perm:[2,3,0,1] row_mask:0xf bank_mask:0xf
	s_nop 1
	v_add_f32_dpp v206, v206, v206 quad_perm:[2,3,0,1] row_mask:0xf bank_mask:0xf
	s_nop 1
	v_add_f32_dpp v207, v207, v207 quad_perm:[2,3,0,1] row_mask:0xf bank_mask:0xf
	s_waitcnt lgkmcnt(7)
	s_waitcnt lgkmcnt(6)
	s_waitcnt lgkmcnt(5)
	s_waitcnt lgkmcnt(4)
	s_waitcnt lgkmcnt(3)
	s_waitcnt lgkmcnt(2)
	s_waitcnt lgkmcnt(1)
	s_waitcnt lgkmcnt(0)
	s_nop 1
	v_add_f32_dpp v200, v200, v200 row_half_mirror row_mask:0xf bank_mask:0xf
	s_nop 1
	v_add_f32_dpp v201, v201, v201 row_half_mirror row_mask:0xf bank_mask:0xf
	s_nop 1
	v_add_f32_dpp v202, v202, v202 row_half_mirror row_mask:0xf bank_mask:0xf
	s_nop 1
	v_add_f32_dpp v203, v203, v203 row_half_mirror row_mask:0xf bank_mask:0xf
	s_nop 1
	v_add_f32_dpp v204, v204, v204 row_half_mirror row_mask:0xf bank_mask:0xf
	s_nop 1
	v_add_f32_dpp v205, v205, v205 row_half_mirror row_mask:0xf bank_mask:0xf
	s_nop 1
	v_add_f32_dpp v206, v206, v206 row_half_mirror row_mask:0xf bank_mask:0xf
	s_nop 1
	v_add_f32_dpp v207, v207, v207 row_half_mirror row_mask:0xf bank_mask:0xf
	s_waitcnt lgkmcnt(7)
	s_waitcnt lgkmcnt(6)
	s_waitcnt lgkmcnt(5)
	s_waitcnt lgkmcnt(4)
	s_waitcnt lgkmcnt(3)
	s_waitcnt lgkmcnt(2)
	s_waitcnt lgkmcnt(1)
	s_waitcnt lgkmcnt(0)
	s_nop 1
	v_add_f32_dpp v200, v200, v200 row_mirror row_mask:0xf bank_mask:0xf
	s_nop 1
	v_add_f32_dpp v201, v201, v201 row_mirror row_mask:0xf bank_mask:0xf
	s_nop 1
	v_add_f32_dpp v202, v202, v202 row_mirror row_mask:0xf bank_mask:0xf
	s_nop 1
	v_add_f32_dpp v203, v203, v203 row_mirror row_mask:0xf bank_mask:0xf
	s_nop 1
	v_add_f32_dpp v204, v204, v204 row_mirror row_mask:0xf bank_mask:0xf
	s_nop 1
	v_add_f32_dpp v205, v205, v205 row_mirror row_mask:0xf bank_mask:0xf
	s_nop 1
	v_add_f32_dpp v206, v206, v206 row_mirror row_mask:0xf bank_mask:0xf
	s_nop 1
	v_add_f32_dpp v207, v207, v207 row_mirror row_mask:0xf bank_mask:0xf
	s_waitcnt lgkmcnt(7)
	s_waitcnt lgkmcnt(6)
	s_waitcnt lgkmcnt(5)
	s_waitcnt lgkmcnt(4)
	s_waitcnt lgkmcnt(3)
	s_waitcnt lgkmcnt(2)
	s_waitcnt lgkmcnt(1)
	s_waitcnt lgkmcnt(0)
	v_mov_b32_e32 v212, v200
	s_nop 1
	v_permlane16_swap_b32_e32 v212, v200
	v_mov_b32_e32 v213, v201
	s_nop 1
	v_permlane16_swap_b32_e32 v213, v201
	v_mov_b32_e32 v214, v202
	s_nop 1
	v_permlane16_swap_b32_e32 v214, v202
	v_mov_b32_e32 v215, v203
	s_nop 1
	v_permlane16_swap_b32_e32 v215, v203
	v_mov_b32_e32 v216, v204
	s_nop 1
	v_permlane16_swap_b32_e32 v216, v204
	v_mov_b32_e32 v217, v205
	s_nop 1
	v_permlane16_swap_b32_e32 v217, v205
	v_mov_b32_e32 v218, v206
	s_nop 1
	v_permlane16_swap_b32_e32 v218, v206
	v_mov_b32_e32 v219, v207
	s_nop 1
	v_permlane16_swap_b32_e32 v219, v207
	s_waitcnt lgkmcnt(7)
	v_add_f32_e32 v200, v200, v212
	s_waitcnt lgkmcnt(6)
	v_add_f32_e32 v201, v201, v213
	s_waitcnt lgkmcnt(5)
	v_add_f32_e32 v202, v202, v214
	s_waitcnt lgkmcnt(4)
	v_add_f32_e32 v203, v203, v215
	s_waitcnt lgkmcnt(3)
	v_add_f32_e32 v204, v204, v216
	s_waitcnt lgkmcnt(2)
	v_add_f32_e32 v205, v205, v217
	s_waitcnt lgkmcnt(1)
	v_add_f32_e32 v206, v206, v218
	s_waitcnt lgkmcnt(0)
	v_add_f32_e32 v207, v207, v219
	v_mov_b32_e32 v212, v200
	s_nop 1
	v_permlane32_swap_b32_e32 v212, v200
	v_mov_b32_e32 v213, v201
	s_nop 1
	v_permlane32_swap_b32_e32 v213, v201
	v_mov_b32_e32 v214, v202
	s_nop 1
	v_permlane32_swap_b32_e32 v214, v202
	v_mov_b32_e32 v215, v203
	s_nop 1
	v_permlane32_swap_b32_e32 v215, v203
	v_mov_b32_e32 v216, v204
	s_nop 1
	v_permlane32_swap_b32_e32 v216, v204
	v_mov_b32_e32 v217, v205
	s_nop 1
	v_permlane32_swap_b32_e32 v217, v205
	v_mov_b32_e32 v218, v206
	s_nop 1
	v_permlane32_swap_b32_e32 v218, v206
	v_mov_b32_e32 v219, v207
	s_nop 1
	v_permlane32_swap_b32_e32 v219, v207
	s_waitcnt lgkmcnt(7)
	v_add_f32_e32 v200, v200, v212
	s_waitcnt lgkmcnt(6)
	v_add_f32_e32 v201, v201, v213
	s_waitcnt lgkmcnt(5)
	v_add_f32_e32 v202, v202, v214
	s_waitcnt lgkmcnt(4)
	v_add_f32_e32 v203, v203, v215
	s_waitcnt lgkmcnt(3)
	v_add_f32_e32 v204, v204, v216
	s_waitcnt lgkmcnt(2)
	v_add_f32_e32 v205, v205, v217
	s_waitcnt lgkmcnt(1)
	v_add_f32_e32 v206, v206, v218
	s_waitcnt lgkmcnt(0)
	v_add_f32_e32 v207, v207, v219
	v_cmp_eq_u32_e32 vcc, 0, v144
	s_and_saveexec_b64 s[10:11], vcc
	s_lshl_b32 s12, s0, 2
	v_mov_b32_e32 v233, s12
	s_mov_b64 s[12:13], s[6:7]
	global_store_dword v233, v200, s[12:13]
	s_add_u32 s12, s12, 0x5800
	s_addc_u32 s13, s13, 0
	global_store_dword v233, v201, s[12:13]
	s_add_u32 s12, s12, 0x5800
	s_addc_u32 s13, s13, 0
	global_store_dword v233, v202, s[12:13]
	s_add_u32 s12, s12, 0x5800
	s_addc_u32 s13, s13, 0
	global_store_dword v233, v203, s[12:13]
	s_add_u32 s12, s12, 0x5800
	s_addc_u32 s13, s13, 0
	global_store_dword v233, v204, s[12:13]
	s_add_u32 s12, s12, 0x5800
	s_addc_u32 s13, s13, 0
	global_store_dword v233, v205, s[12:13]
	s_add_u32 s12, s12, 0x5800
	s_addc_u32 s13, s13, 0
	global_store_dword v233, v206, s[12:13]
	s_add_u32 s12, s12, 0x5800
	s_addc_u32 s13, s13, 0
	global_store_dword v233, v207, s[12:13]
	s_or_b64 exec, exec, s[10:11]
	s_mov_b32 s0, s1
	s_cmpk_lt_i32 s0, 0x1600
	s_cbranch_scc1 .Lb2_loop
